# combo27 + grid barrier flat release (members poll global flag) + one early L2 write-back by the 3/4-th arriver per XCD
# speedup vs baseline: 1.0056x; 1.0056x over previous
; __device__ __forceinline__ unsigned xb_ld(unsigned* p)              { return __hip_atomic_load(p, __ATOMIC_RELAXED, __HIP_MEMORY_SCOPE_AGENT); }
; __device__ __forceinline__ unsigned xb_add(unsigned* p, unsigned v) { return __hip_atomic_fetch_add(p, v, __ATOMIC_RELAXED, __HIP_MEMORY_SCOPE_AGENT); }
; #define XB_SPIN(cond, bar) do { unsigned _sp = 0; while (cond) { __builtin_amdgcn_s_sleep(1); \
;     if ((++_sp & 255u) == 0u) { if (xb_ld(&(bar)[XB_TMO])) break; if (_sp > XB_SPIN_CAP) { atomicAdd(&(bar)[XB_TMO], 1u); break; } } } } while (0)
; __device__ __forceinline__ void xcd_barrier(const XcdBarrier& b, const bool xb_is_leader) {
;     ...
;             const unsigned og = xb_add(&bar[XB_TOP], 1u);
;             const unsigned tg = og / nx;
;             if (og + 1u == (tg + 1u) * nx) xb_add(&bar[XB_TOPGEN], 1u);
;             else XB_SPIN(xb_ld(&bar[XB_TOPGEN]) == tg, bar);
;             __builtin_amdgcn_fence(__ATOMIC_ACQUIRE, "agent");
;             xb_add(&bar[XB_XGEN(b.x)], 1u);
;             asm volatile("s_waitcnt vmcnt(0)" ::: "memory");
;         } else {
;             XB_SPIN(xb_ld(&bar[XB_XGEN(b.x)]) == gen, bar);
.Lxb_noflush_1:
	v_mov_b32_e32 v0, 0x3500
	global_load_dword v0, v0, s[76:77] sc1
	s_add_u32 s10, s76, 0x3500
	s_addc_u32 s11, s77, 0
	s_waitcnt vmcnt(0)
	v_cmp_eq_u32_e32 vcc, v0, v1
	s_and_saveexec_b64 s[8:9], vcc
	s_cbranch_execz .LBB0_217
	s_mov_b32 s2, 1
	s_mov_b64 s[12:13], 0
	v_mov_b32_e32 v0, 0
	s_branch .LBB0_208
